# grid barrier: every workgroup polls the cross-XCD release word; per-XCD relay atomic removed
# baseline (speedup 1.0000x reference)
.LBB0_100:
	s_or_b64 exec, exec, s[6:7]
	s_mov_b64 s[6:7], exec
	v_mbcnt_lo_u32_b32 v0, s6, 0
	v_mbcnt_hi_u32_b32 v0, s7, v0
	v_cmp_eq_u32_e32 vcc, 0, v0
	s_waitcnt vmcnt(0)
	s_and_saveexec_b64 s[10:11], vcc
	s_cbranch_execz .LBB0_102
	s_bcnt1_i32_b64 s6, s[6:7]
	v_mov_b32_e32 v0, 0x2000
	v_mov_b32_e32 v1, s6
.LBB0_102:
	s_or_b64 exec, exec, s[10:11]
	s_waitcnt vmcnt(0)

.LBB0_198:
	s_or_b64 exec, exec, s[6:7]
	s_mov_b64 s[6:7], exec
	v_mbcnt_lo_u32_b32 v0, s6, 0
	v_mbcnt_hi_u32_b32 v0, s7, v0
	v_cmp_eq_u32_e32 vcc, 0, v0
	s_waitcnt vmcnt(0)
	s_and_saveexec_b64 s[10:11], vcc
	s_cbranch_execz .LBB0_200
	s_bcnt1_i32_b64 s6, s[6:7]
	v_mov_b32_e32 v0, 0x2000
	v_mov_b32_e32 v1, s6
.LBB0_200:
	s_or_b64 exec, exec, s[10:11]
	s_waitcnt vmcnt(0)

.LBB0_311:
	s_or_b64 exec, exec, s[6:7]
	s_mov_b64 s[6:7], exec
	v_mbcnt_lo_u32_b32 v0, s6, 0
	v_mbcnt_hi_u32_b32 v0, s7, v0
	v_cmp_eq_u32_e32 vcc, 0, v0
	s_waitcnt vmcnt(0)
	s_and_saveexec_b64 s[10:11], vcc
	s_cbranch_execz .LBB0_313
	s_bcnt1_i32_b64 s6, s[6:7]
	v_mov_b32_e32 v0, 0x2000
	v_mov_b32_e32 v1, s6
.LBB0_313:
	s_or_b64 exec, exec, s[10:11]
	s_waitcnt vmcnt(0)

.LBB0_442:
	s_or_b64 exec, exec, s[4:5]
	s_mov_b64 s[4:5], exec
	v_mbcnt_lo_u32_b32 v0, s4, 0
	v_mbcnt_hi_u32_b32 v0, s5, v0
	v_cmp_eq_u32_e32 vcc, 0, v0
	s_waitcnt vmcnt(0)
	s_and_saveexec_b64 s[6:7], vcc
	s_cbranch_execz .LBB0_444
	s_bcnt1_i32_b64 s4, s[4:5]
	v_mov_b32_e32 v0, 0x2000
	v_mov_b32_e32 v1, s4
.LBB0_444:
	s_or_b64 exec, exec, s[6:7]
	s_waitcnt vmcnt(0)

.LBB0_522:
	s_or_b64 exec, exec, s[6:7]
	s_mov_b64 s[6:7], exec
	v_mbcnt_lo_u32_b32 v0, s6, 0
	v_mbcnt_hi_u32_b32 v0, s7, v0
	v_cmp_eq_u32_e32 vcc, 0, v0
	s_waitcnt vmcnt(0)
	s_and_saveexec_b64 s[10:11], vcc
	s_cbranch_execz .LBB0_524
	s_bcnt1_i32_b64 s6, s[6:7]
	v_mov_b32_e32 v0, 0x2000
	v_mov_b32_e32 v1, s6
.LBB0_524:
	s_or_b64 exec, exec, s[10:11]
	s_waitcnt vmcnt(0)

.LBB0_586:
	s_or_b64 exec, exec, s[6:7]
	s_mov_b64 s[6:7], exec
	v_mbcnt_lo_u32_b32 v0, s6, 0
	v_mbcnt_hi_u32_b32 v0, s7, v0
	v_cmp_eq_u32_e32 vcc, 0, v0
	s_waitcnt vmcnt(0)
	s_and_saveexec_b64 s[10:11], vcc
	s_cbranch_execz .LBB0_588
	s_bcnt1_i32_b64 s6, s[6:7]
	v_mov_b32_e32 v0, 0x2000
	v_mov_b32_e32 v1, s6
.LBB0_588:
	s_or_b64 exec, exec, s[10:11]
	s_waitcnt vmcnt(0)

.LBB0_646:
	s_or_b64 exec, exec, s[6:7]
	s_mov_b64 s[6:7], exec
	v_mbcnt_lo_u32_b32 v0, s6, 0
	v_mbcnt_hi_u32_b32 v0, s7, v0
	v_cmp_eq_u32_e32 vcc, 0, v0
	s_waitcnt vmcnt(0)
	s_and_saveexec_b64 s[10:11], vcc
	s_cbranch_execz .LBB0_648
	s_bcnt1_i32_b64 s6, s[6:7]
	v_mov_b32_e32 v0, 0x2000
	v_mov_b32_e32 v1, s6
.LBB0_648:
	s_or_b64 exec, exec, s[10:11]
	s_waitcnt vmcnt(0)

.LBB0_709:
	s_or_b64 exec, exec, s[6:7]
	s_mov_b64 s[6:7], exec
	v_mbcnt_lo_u32_b32 v0, s6, 0
	v_mbcnt_hi_u32_b32 v0, s7, v0
	v_cmp_eq_u32_e32 vcc, 0, v0
	s_waitcnt vmcnt(0)
	s_and_saveexec_b64 s[10:11], vcc
	s_cbranch_execz .LBB0_711
	s_bcnt1_i32_b64 s6, s[6:7]
	v_mov_b32_e32 v0, 0x2000
	v_mov_b32_e32 v1, s6
.LBB0_711:
	s_or_b64 exec, exec, s[10:11]
	s_waitcnt vmcnt(0)

.LBB0_851:
	s_or_b64 exec, exec, s[4:5]
	s_mov_b64 s[4:5], exec
	v_mbcnt_lo_u32_b32 v0, s4, 0
	v_mbcnt_hi_u32_b32 v0, s5, v0
	v_cmp_eq_u32_e32 vcc, 0, v0
	s_waitcnt vmcnt(0)
	s_and_saveexec_b64 s[6:7], vcc
	s_cbranch_execz .LBB0_853
	s_bcnt1_i32_b64 s4, s[4:5]
	v_mov_b32_e32 v0, 0x2000
	v_mov_b32_e32 v1, s4
.LBB0_853:
	s_or_b64 exec, exec, s[6:7]
	s_waitcnt vmcnt(0)

.LBB0_964:
	s_or_b64 exec, exec, s[6:7]
	s_mov_b64 s[6:7], exec
	v_mbcnt_lo_u32_b32 v0, s6, 0
	v_mbcnt_hi_u32_b32 v0, s7, v0
	v_cmp_eq_u32_e32 vcc, 0, v0
	s_waitcnt vmcnt(0)
	s_and_saveexec_b64 s[10:11], vcc
	s_cbranch_execz .LBB0_966
	s_bcnt1_i32_b64 s6, s[6:7]
	v_mov_b32_e32 v0, 0x2000
	v_mov_b32_e32 v1, s6
.LBB0_966:
	s_or_b64 exec, exec, s[10:11]
	s_waitcnt vmcnt(0)

.LBB0_1095:
	s_or_b64 exec, exec, s[4:5]
	s_mov_b64 s[4:5], exec
	v_mbcnt_lo_u32_b32 v0, s4, 0
	v_mbcnt_hi_u32_b32 v0, s5, v0
	v_cmp_eq_u32_e32 vcc, 0, v0
	s_waitcnt vmcnt(0)
	s_and_saveexec_b64 s[6:7], vcc
	s_cbranch_execz .LBB0_1097
	s_bcnt1_i32_b64 s4, s[4:5]
	v_mov_b32_e32 v0, 0x2000
	v_mov_b32_e32 v1, s4
.LBB0_1097:
	s_or_b64 exec, exec, s[6:7]
	s_waitcnt vmcnt(0)

.LBB0_1192:
	s_or_b64 exec, exec, s[6:7]
	s_mov_b64 s[6:7], exec
	v_mbcnt_lo_u32_b32 v0, s6, 0
	v_mbcnt_hi_u32_b32 v0, s7, v0
	v_cmp_eq_u32_e32 vcc, 0, v0
	s_waitcnt vmcnt(0)
	s_and_saveexec_b64 s[10:11], vcc
	s_cbranch_execz .LBB0_1194
	s_bcnt1_i32_b64 s6, s[6:7]
	v_mov_b32_e32 v0, 0x2000
	v_mov_b32_e32 v1, s6
.LBB0_1194:
	s_or_b64 exec, exec, s[10:11]
	s_waitcnt vmcnt(0)

.LBB0_1319:
	s_or_b64 exec, exec, s[4:5]
	s_mov_b64 s[4:5], exec
	v_mbcnt_lo_u32_b32 v0, s4, 0
	v_mbcnt_hi_u32_b32 v0, s5, v0
	v_cmp_eq_u32_e32 vcc, 0, v0
	s_waitcnt vmcnt(0)
	s_and_saveexec_b64 s[6:7], vcc
	s_cbranch_execz .LBB0_1321
	s_bcnt1_i32_b64 s4, s[4:5]
	v_mov_b32_e32 v0, 0x2000
	v_mov_b32_e32 v1, s4
.LBB0_1321:
	s_or_b64 exec, exec, s[6:7]
	s_waitcnt vmcnt(0)

.LBB0_1393:
	s_or_b64 exec, exec, s[4:5]
	s_mov_b64 s[4:5], exec
	v_mbcnt_lo_u32_b32 v0, s4, 0
	v_mbcnt_hi_u32_b32 v0, s5, v0
	v_cmp_eq_u32_e32 vcc, 0, v0
	s_waitcnt vmcnt(0)
	s_and_saveexec_b64 s[6:7], vcc
	s_cbranch_execz .LBB0_1395
	s_bcnt1_i32_b64 s4, s[4:5]
	v_mov_b32_e32 v0, 0x2000
	v_mov_b32_e32 v1, s4
.LBB0_1395:
	s_or_b64 exec, exec, s[6:7]
	s_waitcnt vmcnt(0)

.LBB0_1474:
	s_or_b64 exec, exec, s[6:7]
	s_mov_b64 s[6:7], exec
	v_mbcnt_lo_u32_b32 v0, s6, 0
	v_mbcnt_hi_u32_b32 v0, s7, v0
	v_cmp_eq_u32_e32 vcc, 0, v0
	s_waitcnt vmcnt(0)
	s_and_saveexec_b64 s[10:11], vcc
	s_cbranch_execz .LBB0_1476
	s_bcnt1_i32_b64 s6, s[6:7]
	v_mov_b32_e32 v0, 0x2000
	v_mov_b32_e32 v1, s6
.LBB0_1476:
	s_or_b64 exec, exec, s[10:11]
	s_waitcnt vmcnt(0)

.LBB0_1571:
	s_or_b64 exec, exec, s[4:5]
	s_mov_b64 s[4:5], exec
	v_mbcnt_lo_u32_b32 v0, s4, 0
	v_mbcnt_hi_u32_b32 v0, s5, v0
	v_cmp_eq_u32_e32 vcc, 0, v0
	s_waitcnt vmcnt(0)
	s_and_saveexec_b64 s[6:7], vcc
	s_cbranch_execz .LBB0_1573
	s_bcnt1_i32_b64 s4, s[4:5]
	v_mov_b32_e32 v0, 0x2000
	v_mov_b32_e32 v1, s4
.LBB0_1573:
	s_or_b64 exec, exec, s[6:7]
	s_waitcnt vmcnt(0)

.LBB0_1642:
	s_or_b64 exec, exec, s[6:7]
	s_mov_b64 s[6:7], exec
	v_mbcnt_lo_u32_b32 v0, s6, 0
	v_mbcnt_hi_u32_b32 v0, s7, v0
	v_cmp_eq_u32_e32 vcc, 0, v0
	s_waitcnt vmcnt(0)
	s_and_saveexec_b64 s[10:11], vcc
	s_cbranch_execz .LBB0_1644
	s_bcnt1_i32_b64 s6, s[6:7]
	v_mov_b32_e32 v0, 0x2000
	v_mov_b32_e32 v1, s6
.LBB0_1644:
	s_or_b64 exec, exec, s[10:11]
	s_waitcnt vmcnt(0)
